# snake_peel_relu2trim
# speedup vs baseline: 1.0125x; 1.0065x over previous
.Lpeel_exit_w1:
	s_lshl_b32 s1, s41, 5
	v_max_f32_e32 v122, 0, v122
	s_add_i32 s12, s1, s42
	v_mul_f32_e32 v142, v122, v122
	v_max_f32_e32 v123, 0, v123
	v_max_f32_e32 v124, 0, v124
	s_ashr_i32 s13, s12, 31
	v_max_f32_e32 v122, 0, v127
	v_mul_f32_e32 v127, v123, v123
	v_max_f32_e32 v123, v128, v128
	v_mul_f32_e32 v128, v124, v124
	s_lshl_b64 s[12:13], s[12:13], 17
	v_max_f32_e32 v126, 0, v126
	v_mul_f32_e32 v122, v122, v122
	v_max_f32_e32 v123, 0, v123
	v_max_f32_e32 v124, 0, v129
	v_max_f32_e32 v125, 0, v125
	v_lshl_add_u64 v[138:139], v[136:137], 0, s[12:13]
	v_mul_f32_e32 v126, v126, v126
	v_mul_f32_e32 v123, v123, v123
	v_mul_f32_e32 v124, v124, v124
	v_mul_f32_e32 v125, v125, v125
	v_cvt_pk_bf16_f32 v122, v126, v122
	v_max_f32_e32 v114, 0, v114
	v_cvt_pk_bf16_f32 v123, v123, v124
	v_cvt_pk_bf16_f32 v124, v142, v127
	v_cvt_pk_bf16_f32 v125, v128, v125
	global_store_dwordx4 v[138:139], v[122:125], off
	v_max_f32_e32 v115, 0, v115
	v_max_f32_e32 v116, 0, v116
	v_mul_f32_e32 v122, v114, v114
	v_max_f32_e32 v114, 0, v119
	v_mul_f32_e32 v119, v115, v115
	v_max_f32_e32 v115, v120, v120
	v_mul_f32_e32 v120, v116, v116
	v_max_f32_e32 v118, 0, v118
	v_mul_f32_e32 v114, v114, v114
	v_max_f32_e32 v115, 0, v115
	v_max_f32_e32 v116, 0, v121
	v_max_f32_e32 v117, 0, v117
	v_mul_f32_e32 v118, v118, v118
	v_mul_f32_e32 v115, v115, v115
	v_mul_f32_e32 v116, v116, v116
	v_mul_f32_e32 v117, v117, v117
	v_cvt_pk_bf16_f32 v114, v118, v114
	v_max_f32_e32 v106, 0, v106
	v_cvt_pk_bf16_f32 v115, v115, v116
	v_cvt_pk_bf16_f32 v116, v122, v119
	v_cvt_pk_bf16_f32 v117, v120, v117
	global_store_dwordx4 v[138:139], v[114:117], off offset:256
	s_nop 0
	v_max_f32_e32 v107, 0, v107
	v_mul_f32_e32 v114, v106, v106
	v_max_f32_e32 v108, 0, v108
	v_max_f32_e32 v110, 0, v110
	v_max_f32_e32 v106, 0, v111
	v_mul_f32_e32 v111, v107, v107
	v_max_f32_e32 v107, v112, v112
	v_mul_f32_e32 v112, v108, v108
	v_mul_f32_e32 v110, v110, v110
	v_mul_f32_e32 v106, v106, v106
	v_max_f32_e32 v107, 0, v107
	v_max_f32_e32 v108, 0, v113
	s_movk_i32 s1, 0x2000
	v_mul_f32_e32 v107, v107, v107
	v_max_f32_e32 v109, 0, v109
	v_mul_f32_e32 v108, v108, v108
	v_cvt_pk_bf16_f32 v106, v110, v106
	v_add_co_u32_e32 v110, vcc, s1, v138
	v_mul_f32_e32 v109, v109, v109
	v_cvt_pk_bf16_f32 v107, v107, v108
	v_cvt_pk_bf16_f32 v108, v114, v111
	v_addc_co_u32_e32 v111, vcc, 0, v139, vcc
	v_max_f32_e32 v98, 0, v98
	v_cvt_pk_bf16_f32 v109, v112, v109
	global_store_dwordx4 v[110:111], v[106:109], off
	v_max_f32_e32 v99, 0, v99
	v_max_f32_e32 v100, 0, v100
	v_mul_f32_e32 v106, v98, v98
	v_max_f32_e32 v98, 0, v103
	v_mul_f32_e32 v103, v99, v99
	v_max_f32_e32 v99, v104, v104
	v_mul_f32_e32 v104, v100, v100
	v_max_f32_e32 v102, 0, v102
	v_mul_f32_e32 v98, v98, v98
	v_max_f32_e32 v99, 0, v99
	v_max_f32_e32 v100, 0, v105
	v_max_f32_e32 v101, 0, v101
	v_mul_f32_e32 v102, v102, v102
	v_mul_f32_e32 v99, v99, v99
	v_mul_f32_e32 v100, v100, v100
	v_mul_f32_e32 v101, v101, v101
	v_cvt_pk_bf16_f32 v98, v102, v98
	v_max_f32_e32 v90, 0, v90
	v_cvt_pk_bf16_f32 v99, v99, v100
	v_cvt_pk_bf16_f32 v100, v106, v103
	v_cvt_pk_bf16_f32 v101, v104, v101
	global_store_dwordx4 v[110:111], v[98:101], off offset:256
	s_nop 0
	v_max_f32_e32 v91, 0, v91
	v_mul_f32_e32 v98, v90, v90
	v_max_f32_e32 v92, 0, v92
	v_max_f32_e32 v94, 0, v94
	v_max_f32_e32 v90, 0, v95
	v_mul_f32_e32 v95, v91, v91
	v_max_f32_e32 v91, v96, v96
	v_mul_f32_e32 v96, v92, v92
	v_mul_f32_e32 v94, v94, v94
	v_mul_f32_e32 v90, v90, v90
	v_max_f32_e32 v91, 0, v91
	v_max_f32_e32 v92, 0, v97
	s_movk_i32 s1, 0x4000
	v_mul_f32_e32 v91, v91, v91
	v_max_f32_e32 v93, 0, v93
	v_mul_f32_e32 v92, v92, v92
	v_cvt_pk_bf16_f32 v90, v94, v90
	v_add_co_u32_e32 v94, vcc, s1, v138
	v_mul_f32_e32 v93, v93, v93
	v_cvt_pk_bf16_f32 v91, v91, v92
	v_cvt_pk_bf16_f32 v92, v98, v95
	v_addc_co_u32_e32 v95, vcc, 0, v139, vcc
	v_max_f32_e32 v82, 0, v82
	v_cvt_pk_bf16_f32 v93, v96, v93
	global_store_dwordx4 v[94:95], v[90:93], off
	v_max_f32_e32 v83, 0, v83
	v_max_f32_e32 v84, 0, v84
	v_mul_f32_e32 v90, v82, v82
	v_max_f32_e32 v82, 0, v87
	v_mul_f32_e32 v87, v83, v83
	v_max_f32_e32 v83, v88, v88
	v_mul_f32_e32 v88, v84, v84
	v_max_f32_e32 v86, 0, v86
	v_mul_f32_e32 v82, v82, v82
	v_max_f32_e32 v83, 0, v83
	v_max_f32_e32 v84, 0, v89
	v_max_f32_e32 v85, 0, v85
	v_mul_f32_e32 v86, v86, v86
	v_mul_f32_e32 v83, v83, v83
	v_mul_f32_e32 v84, v84, v84
	v_mul_f32_e32 v85, v85, v85
	v_cvt_pk_bf16_f32 v82, v86, v82
	v_max_f32_e32 v74, 0, v74
	v_cvt_pk_bf16_f32 v83, v83, v84
	v_cvt_pk_bf16_f32 v84, v90, v87
	v_cvt_pk_bf16_f32 v85, v88, v85
	global_store_dwordx4 v[94:95], v[82:85], off offset:256
	s_nop 0
	v_max_f32_e32 v75, 0, v75
	v_mul_f32_e32 v82, v74, v74
	v_max_f32_e32 v76, 0, v76
	v_max_f32_e32 v78, 0, v78
	v_max_f32_e32 v74, 0, v79
	v_mul_f32_e32 v79, v75, v75
	v_max_f32_e32 v75, v80, v80
	v_mul_f32_e32 v80, v76, v76
	v_mul_f32_e32 v78, v78, v78
	v_mul_f32_e32 v74, v74, v74
	v_max_f32_e32 v75, 0, v75
	v_max_f32_e32 v76, 0, v81
	s_movk_i32 s1, 0x6000
	v_mul_f32_e32 v75, v75, v75
	v_max_f32_e32 v77, 0, v77
	v_mul_f32_e32 v76, v76, v76
	v_cvt_pk_bf16_f32 v74, v78, v74
	v_add_co_u32_e32 v78, vcc, s1, v138
	v_mul_f32_e32 v77, v77, v77
	v_cvt_pk_bf16_f32 v75, v75, v76
	v_cvt_pk_bf16_f32 v76, v82, v79
	v_addc_co_u32_e32 v79, vcc, 0, v139, vcc
	v_max_f32_e32 v66, 0, v66
	v_cvt_pk_bf16_f32 v77, v80, v77
	global_store_dwordx4 v[78:79], v[74:77], off
	v_max_f32_e32 v67, 0, v67
	v_max_f32_e32 v68, 0, v68
	v_mul_f32_e32 v74, v66, v66
	v_max_f32_e32 v66, 0, v71
	v_mul_f32_e32 v71, v67, v67
	v_max_f32_e32 v67, v72, v72
	v_mul_f32_e32 v72, v68, v68
	v_max_f32_e32 v70, 0, v70
	v_mul_f32_e32 v66, v66, v66
	v_max_f32_e32 v67, 0, v67
	v_max_f32_e32 v68, 0, v73
	v_max_f32_e32 v69, 0, v69
	v_mul_f32_e32 v70, v70, v70
	v_mul_f32_e32 v67, v67, v67
	v_mul_f32_e32 v68, v68, v68
	v_mul_f32_e32 v69, v69, v69
	v_cvt_pk_bf16_f32 v66, v70, v66
	v_max_f32_e32 v58, 0, v58
	v_cvt_pk_bf16_f32 v67, v67, v68
	v_cvt_pk_bf16_f32 v68, v74, v71
	v_cvt_pk_bf16_f32 v69, v72, v69
	global_store_dwordx4 v[78:79], v[66:69], off offset:256
	s_nop 0
	v_max_f32_e32 v59, 0, v59
	v_mul_f32_e32 v66, v58, v58
	v_max_f32_e32 v60, 0, v60
	v_max_f32_e32 v62, 0, v62
	v_max_f32_e32 v58, 0, v63
	v_mul_f32_e32 v63, v59, v59
	v_max_f32_e32 v59, v64, v64
	v_mul_f32_e32 v64, v60, v60
	v_mul_f32_e32 v62, v62, v62
	v_mul_f32_e32 v58, v58, v58
	v_max_f32_e32 v59, 0, v59
	v_max_f32_e32 v60, 0, v65
	s_mov_b32 s1, 0x10000
	v_mul_f32_e32 v59, v59, v59
	v_max_f32_e32 v61, 0, v61
	v_mul_f32_e32 v60, v60, v60
	v_cvt_pk_bf16_f32 v58, v62, v58
	v_add_co_u32_e32 v62, vcc, s1, v138
	v_mul_f32_e32 v61, v61, v61
	v_cvt_pk_bf16_f32 v59, v59, v60
	v_cvt_pk_bf16_f32 v60, v66, v63
	v_addc_co_u32_e32 v63, vcc, 0, v139, vcc
	v_max_f32_e32 v50, 0, v50
	v_cvt_pk_bf16_f32 v61, v64, v61
	global_store_dwordx4 v[62:63], v[58:61], off
	v_max_f32_e32 v51, 0, v51
	v_max_f32_e32 v52, 0, v52
	v_mul_f32_e32 v58, v50, v50
	v_max_f32_e32 v50, 0, v55
	v_mul_f32_e32 v55, v51, v51
	v_max_f32_e32 v51, v56, v56
	v_mul_f32_e32 v56, v52, v52
	v_max_f32_e32 v54, 0, v54
	v_mul_f32_e32 v50, v50, v50
	v_max_f32_e32 v51, 0, v51
	v_max_f32_e32 v52, 0, v57
	v_max_f32_e32 v53, 0, v53
	v_mul_f32_e32 v54, v54, v54
	v_mul_f32_e32 v51, v51, v51
	v_mul_f32_e32 v52, v52, v52
	v_mul_f32_e32 v53, v53, v53
	v_cvt_pk_bf16_f32 v50, v54, v50
	v_max_f32_e32 v42, 0, v42
	v_cvt_pk_bf16_f32 v51, v51, v52
	v_cvt_pk_bf16_f32 v52, v58, v55
	v_cvt_pk_bf16_f32 v53, v56, v53
	global_store_dwordx4 v[62:63], v[50:53], off offset:256
	s_nop 0
	v_max_f32_e32 v43, 0, v43
	v_mul_f32_e32 v50, v42, v42
	v_max_f32_e32 v44, 0, v44
	v_max_f32_e32 v46, 0, v46
	v_max_f32_e32 v42, 0, v47
	v_mul_f32_e32 v47, v43, v43
	v_max_f32_e32 v43, v48, v48
	v_mul_f32_e32 v48, v44, v44
	v_mul_f32_e32 v46, v46, v46
	v_mul_f32_e32 v42, v42, v42
	v_max_f32_e32 v43, 0, v43
	v_max_f32_e32 v44, 0, v49
	s_mov_b32 s1, 0x12000
	v_mul_f32_e32 v43, v43, v43
	v_max_f32_e32 v45, 0, v45
	v_mul_f32_e32 v44, v44, v44
	v_cvt_pk_bf16_f32 v42, v46, v42
	v_add_co_u32_e32 v46, vcc, s1, v138
	v_mul_f32_e32 v45, v45, v45
	v_cvt_pk_bf16_f32 v43, v43, v44
	v_cvt_pk_bf16_f32 v44, v50, v47
	v_addc_co_u32_e32 v47, vcc, 0, v139, vcc
	v_max_f32_e32 v34, 0, v34
	v_cvt_pk_bf16_f32 v45, v48, v45
	global_store_dwordx4 v[46:47], v[42:45], off
	v_max_f32_e32 v35, 0, v35
	v_max_f32_e32 v36, 0, v36
	v_mul_f32_e32 v42, v34, v34
	v_max_f32_e32 v34, 0, v39
	v_mul_f32_e32 v39, v35, v35
	v_max_f32_e32 v35, v40, v40
	v_mul_f32_e32 v40, v36, v36
	v_max_f32_e32 v38, 0, v38
	v_mul_f32_e32 v34, v34, v34
	v_max_f32_e32 v35, 0, v35
	v_max_f32_e32 v36, 0, v41
	v_max_f32_e32 v37, 0, v37
	v_mul_f32_e32 v38, v38, v38
	v_mul_f32_e32 v35, v35, v35
	v_mul_f32_e32 v36, v36, v36
	v_mul_f32_e32 v37, v37, v37
	v_cvt_pk_bf16_f32 v34, v38, v34
	v_max_f32_e32 v26, 0, v26
	v_cvt_pk_bf16_f32 v35, v35, v36
	v_cvt_pk_bf16_f32 v36, v42, v39
	v_cvt_pk_bf16_f32 v37, v40, v37
	global_store_dwordx4 v[46:47], v[34:37], off offset:256
	s_nop 0
	v_max_f32_e32 v27, 0, v27
	v_mul_f32_e32 v34, v26, v26
	v_max_f32_e32 v28, 0, v28
	v_max_f32_e32 v30, 0, v30
	v_max_f32_e32 v26, 0, v31
	v_mul_f32_e32 v31, v27, v27
	v_max_f32_e32 v27, v32, v32
	v_mul_f32_e32 v32, v28, v28
	v_mul_f32_e32 v30, v30, v30
	v_mul_f32_e32 v26, v26, v26
	v_max_f32_e32 v27, 0, v27
	v_max_f32_e32 v28, 0, v33
	s_mov_b32 s1, 0x14000
	v_mul_f32_e32 v27, v27, v27
	v_max_f32_e32 v29, 0, v29
	v_mul_f32_e32 v28, v28, v28
	v_cvt_pk_bf16_f32 v26, v30, v26
	v_add_co_u32_e32 v30, vcc, s1, v138
	v_mul_f32_e32 v29, v29, v29
	v_cvt_pk_bf16_f32 v27, v27, v28
	v_cvt_pk_bf16_f32 v28, v34, v31
	v_addc_co_u32_e32 v31, vcc, 0, v139, vcc
	v_max_f32_e32 v18, 0, v18
	v_cvt_pk_bf16_f32 v29, v32, v29
	global_store_dwordx4 v[30:31], v[26:29], off
	v_max_f32_e32 v19, 0, v19
	v_max_f32_e32 v20, 0, v20
	v_mul_f32_e32 v26, v18, v18
	v_max_f32_e32 v18, 0, v23
	v_mul_f32_e32 v23, v19, v19
	v_max_f32_e32 v19, v24, v24
	v_mul_f32_e32 v24, v20, v20
	v_max_f32_e32 v22, 0, v22
	v_mul_f32_e32 v18, v18, v18
	v_max_f32_e32 v19, 0, v19
	v_max_f32_e32 v20, 0, v25
	v_max_f32_e32 v21, 0, v21
	v_mul_f32_e32 v22, v22, v22
	v_mul_f32_e32 v19, v19, v19
	v_mul_f32_e32 v20, v20, v20
	v_mul_f32_e32 v21, v21, v21
	v_cvt_pk_bf16_f32 v18, v22, v18
	v_max_f32_e32 v10, 0, v10
	v_cvt_pk_bf16_f32 v19, v19, v20
	v_cvt_pk_bf16_f32 v20, v26, v23
	v_cvt_pk_bf16_f32 v21, v24, v21
	global_store_dwordx4 v[30:31], v[18:21], off offset:256
	s_nop 0
	v_max_f32_e32 v11, 0, v11
	v_mul_f32_e32 v18, v10, v10
	v_max_f32_e32 v12, 0, v12
	v_max_f32_e32 v14, 0, v14
	v_max_f32_e32 v10, 0, v15
	v_mul_f32_e32 v15, v11, v11
	v_max_f32_e32 v11, v16, v16
	v_mul_f32_e32 v16, v12, v12
	v_mul_f32_e32 v14, v14, v14
	v_mul_f32_e32 v10, v10, v10
	v_max_f32_e32 v11, 0, v11
	v_max_f32_e32 v12, 0, v17
	s_mov_b32 s1, 0x16000
	v_mul_f32_e32 v11, v11, v11
	v_max_f32_e32 v13, 0, v13
	v_mul_f32_e32 v12, v12, v12
	v_cvt_pk_bf16_f32 v10, v14, v10
	v_add_co_u32_e32 v14, vcc, s1, v138
	v_mul_f32_e32 v13, v13, v13
	v_cvt_pk_bf16_f32 v11, v11, v12
	v_cvt_pk_bf16_f32 v12, v18, v15
	v_addc_co_u32_e32 v15, vcc, 0, v139, vcc
	v_max_f32_e32 v2, 0, v2
	v_max_f32_e32 v3, 0, v3
	v_max_f32_e32 v4, 0, v4
	v_cvt_pk_bf16_f32 v13, v16, v13
	global_store_dwordx4 v[14:15], v[10:13], off
	s_nop 1
	v_mul_f32_e32 v10, v2, v2
	v_max_f32_e32 v2, v7, v7
	v_mul_f32_e32 v7, v3, v3
	v_max_f32_e32 v3, v8, v8
	v_mul_f32_e32 v8, v4, v4
	v_max_f32_e32 v2, 0, v2
	v_max_f32_e32 v3, 0, v3
	v_max_f32_e32 v4, 0, v9
	v_max_f32_e32 v5, 0, v5
	v_max_f32_e32 v6, 0, v6
	v_mul_f32_e32 v2, v2, v2
	v_mul_f32_e32 v3, v3, v3
	v_mul_f32_e32 v4, v4, v4
	v_mul_f32_e32 v5, v5, v5
	s_and_b64 vcc, exec, s[4:5]
	s_mov_b32 s42, s0
	s_mov_b32 s41, s6
	s_mov_b64 s[18:19], s[8:9]
	s_mov_b64 s[12:13], s[10:11]
	v_mul_f32_e32 v6, v6, v6
	v_cvt_pk_bf16_f32 v2, v6, v2
	v_cvt_pk_bf16_f32 v3, v3, v4
	v_cvt_pk_bf16_f32 v4, v10, v7
	v_cvt_pk_bf16_f32 v5, v8, v5
	global_store_dwordx4 v[14:15], v[2:5], off offset:256
	s_cbranch_vccz .LBB0_960
	s_waitcnt vmcnt(0)
	s_cmpk_gt_u32 s26, 0xff
	s_cbranch_scc1 .LBB0_967
	s_barrier
